# GEMM K-loops: block-ending barrier issued eight MFMAs early; next block raises priority after its eighth MFMA
# baseline (speedup 1.0000x reference)
; #define PG8_STAGE(bufoff, gbase, voff) do { _Pragma("unroll") for (int _i = 0; _i < 2; ++_i) \
;         __builtin_amdgcn_global_load_lds((const unsigned*)((const char*)(gbase) + (voff)[_i]), (PG8_LAS unsigned*)(lds + (bufoff) + ldsw + _i * 8192), 16, 0, 0); } while (0)
; #define PG8_LDA(dst, b, h) do { _Pragma("unroll") for (int m = 0; m < 4; ++m) _Pragma("unroll") for (int k = 0; k < 2; ++k) dst[m][k] = *(const PG8_LAS bf16x8*)(lds + PG8_SA(b, h) + aoff + m * 2048 + k * 1024); } while (0)
; #define PG8_LDB(dst, b, h) do { _Pragma("unroll") for (int n = 0; n < 2; ++n) _Pragma("unroll") for (int k = 0; k < 2; ++k) dst[n][k] = *(const PG8_LAS bf16x8*)(lds + PG8_SB(b, h) + boff + n * 2048 + k * 1024); } while (0)
; #define PG8_MMA(ai, bj, At, Bt) do { __builtin_amdgcn_s_setprio(1); _Pragma("unroll") for (int m = 0; m < 4; ++m) _Pragma("unroll") for (int n = 0; n < 2; ++n) _Pragma("unroll") for (int k = 0; k < 2; ++k) \
;         acc[ai][bj][m][n] = __builtin_amdgcn_mfma_f32_16x16x32_bf16(Bt[n][k], At[m][k], acc[ai][bj][m][n], 0, 0, 0); __builtin_amdgcn_s_setprio(0); } while (0)
; #define PG8_WAIT_V(n) asm volatile("s_waitcnt vmcnt(" #n ")" ::: "memory")
; #define PG8_WAIT_L(n) asm volatile("s_waitcnt lgkmcnt(" #n ")" ::: "memory")
; template <class Epi, class Sched, bool ALIGN_EPI = false, bool SP2 = false>
; __device__ __forceinline__ void gemm_phase(PG8_LAS unsigned char* lds, const Gemm g, const Sched& S, const Epi& E) {
;     ...
;             const bool last = (t == nt - 2);
;             const char* a1 = cA + (size_t)(t + 1) * kstep;
;             const char* a2 = last ? nA : cA + (size_t)(t + 2) * kstep; const char* b2 = last ? nB : cB + (size_t)(t + 2) * kstep;
;             const char* a3 = a2 + kstep; const char* b3 = b2 + kstep;
;             if (last && has_next) S.a_ready(nxt);
;             if constexpr (SP2) {
;             PG8_LDB(B0, 0, 0); PG8_LDB(B1, 0, 1); PG8_SCHED; PG8_LDA(At, 0, 0); PG8_STAGE(PG8_SA(1, 1), a1 + hstep, voffA);
;             PG8_WAIT_V(8); PG8_WAIT_L(0); PG8_BAR; PG8_MMA(0, 0, At, B0); PG8_MMA(0, 1, At, B1); PG8_BAR; PG8_SCHED;
;             PG8_LDA(At, 0, 1); PG8_STAGE(PG8_SB(0, 0), b2, voffB); PG8_STAGE(PG8_SB(0, 1), b2 + hstep, voffB); PG8_STAGE(PG8_SA(0, 0), a2, voffA);
;             PG8_WAIT_V(8); PG8_WAIT_L(0); PG8_BAR; PG8_MMA(1, 0, At, B0); PG8_MMA(1, 1, At, B1); PG8_BAR; PG8_SCHED;
.LBB0_165:
	s_add_u32 s16, s8, 0xfffc0080
	s_addc_u32 s17, s9, -1
	s_add_i32 s18, 0, 0x10000
	s_cmp_eq_u32 s55, 12
	s_cselect_b32 s43, s14, s17
	s_cselect_b32 s42, s15, s16
	v_add_u32_e32 v0, s18, v194
	s_cselect_b32 s41, s13, s54
	s_cselect_b32 s40, s25, s53
	s_add_i32 s19, 0, 0x14000
	ds_read_b128 v[136:139], v0
	ds_read_b128 v[140:143], v0 offset:1024
	ds_read_b128 v[144:147], v0 offset:2048
	ds_read_b128 v[148:151], v0 offset:3072
	v_add_u32_e32 v0, s19, v194
	ds_read_b128 v[152:155], v0
	ds_read_b128 v[186:189], v0 offset:1024
	ds_read_b128 v[190:193], v0 offset:2048
	ds_read_b128 v[198:201], v0 offset:3072
	v_lshl_add_u64 v[2:3], s[8:9], 0, v[182:183]
	s_add_i32 m0, s45, 0xc000
	ds_read_b128 v[210:213], v196
	ds_read_b128 v[214:217], v196 offset:1024
	ds_read_b128 v[218:221], v196 offset:2048
	ds_read_b128 v[222:225], v196 offset:3072
	ds_read_b128 v[226:229], v196 offset:4096
	ds_read_b128 v[230:233], v196 offset:5120
	ds_read_b128 v[234:237], v196 offset:6144
	ds_read_b128 v[238:241], v196 offset:7168
	global_load_lds_dwordx4 v[2:3], off
	v_lshl_add_u64 v[2:3], s[8:9], 0, v[184:185]
	s_add_i32 m0, s45, 0xe000
	s_nop 0
	global_load_lds_dwordx4 v[2:3], off
	s_waitcnt vmcnt(8)
	s_waitcnt lgkmcnt(0)
	s_barrier
	s_waitcnt lgkmcnt(0)
	v_mfma_f32_16x16x32_bf16 v[132:135], v[136:139], v[210:213], v[132:135]
	v_mfma_f32_16x16x32_bf16 v[128:131], v[144:147], v[210:213], v[128:131]
	v_mfma_f32_16x16x32_bf16 v[124:127], v[136:139], v[218:221], v[124:127]
	v_mfma_f32_16x16x32_bf16 v[120:123], v[144:147], v[218:221], v[120:123]
	v_mfma_f32_16x16x32_bf16 v[116:119], v[136:139], v[226:229], v[116:119]
	v_mfma_f32_16x16x32_bf16 v[112:115], v[144:147], v[226:229], v[112:115]
	v_mfma_f32_16x16x32_bf16 v[108:111], v[136:139], v[234:237], v[108:111]
	v_mfma_f32_16x16x32_bf16 v[104:107], v[144:147], v[234:237], v[104:107]
	s_setprio 1
	v_mfma_f32_16x16x32_bf16 v[132:135], v[140:143], v[214:217], v[132:135]
	v_mfma_f32_16x16x32_bf16 v[128:131], v[148:151], v[214:217], v[128:131]
	v_mfma_f32_16x16x32_bf16 v[124:127], v[140:143], v[222:225], v[124:127]
	v_mfma_f32_16x16x32_bf16 v[120:123], v[148:151], v[222:225], v[120:123]
	v_mfma_f32_16x16x32_bf16 v[116:119], v[140:143], v[230:233], v[116:119]
	v_mfma_f32_16x16x32_bf16 v[112:115], v[148:151], v[230:233], v[112:115]
	v_mfma_f32_16x16x32_bf16 v[108:111], v[140:143], v[238:241], v[108:111]
	v_mfma_f32_16x16x32_bf16 v[104:107], v[148:151], v[238:241], v[104:107]
	s_setprio 0
	s_setprio 1
	v_mfma_f32_16x16x32_bf16 v[84:87], v[152:155], v[210:213], v[84:87]
	v_mfma_f32_16x16x32_bf16 v[76:79], v[190:193], v[210:213], v[76:79]
	v_mfma_f32_16x16x32_bf16 v[68:71], v[152:155], v[218:221], v[68:71]
	v_mfma_f32_16x16x32_bf16 v[64:67], v[190:193], v[218:221], v[64:67]
	v_mfma_f32_16x16x32_bf16 v[52:55], v[152:155], v[226:229], v[52:55]
	v_mfma_f32_16x16x32_bf16 v[48:51], v[190:193], v[226:229], v[48:51]
	v_mfma_f32_16x16x32_bf16 v[44:47], v[152:155], v[234:237], v[44:47]
	v_mfma_f32_16x16x32_bf16 v[40:43], v[190:193], v[234:237], v[40:43]
	s_barrier
	v_mfma_f32_16x16x32_bf16 v[84:87], v[186:189], v[214:217], v[84:87]
	v_mfma_f32_16x16x32_bf16 v[76:79], v[198:201], v[214:217], v[76:79]
	v_mfma_f32_16x16x32_bf16 v[68:71], v[186:189], v[222:225], v[68:71]
	v_mfma_f32_16x16x32_bf16 v[64:67], v[198:201], v[222:225], v[64:67]
	v_mfma_f32_16x16x32_bf16 v[52:55], v[186:189], v[230:233], v[52:55]
	v_mfma_f32_16x16x32_bf16 v[48:51], v[198:201], v[230:233], v[48:51]
	v_mfma_f32_16x16x32_bf16 v[44:47], v[186:189], v[238:241], v[44:47]
	v_mfma_f32_16x16x32_bf16 v[40:43], v[198:201], v[238:241], v[40:43]
	s_setprio 0
	s_add_i32 s16, s18, s44
	v_lshl_add_u64 v[2:3], s[40:41], 0, v[162:163]
	s_mov_b32 m0, s16
	ds_read_b128 v[210:213], v196 offset:16384
	ds_read_b128 v[214:217], v196 offset:17408
	ds_read_b128 v[218:221], v196 offset:18432
	ds_read_b128 v[222:225], v196 offset:19456
	ds_read_b128 v[226:229], v196 offset:20480
	ds_read_b128 v[230:233], v196 offset:21504
	ds_read_b128 v[234:237], v196 offset:22528
	ds_read_b128 v[238:241], v196 offset:23552
	global_load_lds_dwordx4 v[2:3], off
	s_add_i32 m0, s16, 0x2000
	s_add_u32 s16, s40, 0x40000
	v_lshl_add_u64 v[156:157], s[40:41], 0, v[158:159]
	s_addc_u32 s17, s41, 0
	s_add_i32 s18, s19, s44
	global_load_lds_dwordx4 v[156:157], off
	v_lshl_add_u64 v[242:243], s[16:17], 0, v[162:163]
	s_mov_b32 m0, s18
	v_lshl_add_u64 v[244:245], s[42:43], 0, v[160:161]
	global_load_lds_dwordx4 v[242:243], off
	v_lshl_add_u64 v[242:243], s[16:17], 0, v[158:159]
	s_add_i32 m0, s18, 0x2000
	s_nop 0
	global_load_lds_dwordx4 v[242:243], off
	v_lshl_add_u64 v[242:243], s[42:43], 0, v[178:179]
	s_waitcnt vmcnt(6)
	s_waitcnt lgkmcnt(0)
	s_barrier
	s_waitcnt lgkmcnt(0)
	v_mfma_f32_16x16x32_bf16 v[100:103], v[136:139], v[210:213], v[100:103]
	v_mfma_f32_16x16x32_bf16 v[96:99], v[144:147], v[210:213], v[96:99]
	v_mfma_f32_16x16x32_bf16 v[92:95], v[136:139], v[218:221], v[92:95]
	s_mov_b32 m0, s45
	v_mfma_f32_16x16x32_bf16 v[88:91], v[144:147], v[218:221], v[88:91]
	global_load_lds_dwordx4 v[242:243], off
	v_mfma_f32_16x16x32_bf16 v[80:83], v[136:139], v[226:229], v[80:83]
	v_mfma_f32_16x16x32_bf16 v[72:75], v[144:147], v[226:229], v[72:75]
	v_mfma_f32_16x16x32_bf16 v[60:63], v[136:139], v[234:237], v[60:63]
	v_mfma_f32_16x16x32_bf16 v[56:59], v[144:147], v[234:237], v[56:59]
	s_setprio 1
	v_mfma_f32_16x16x32_bf16 v[100:103], v[140:143], v[214:217], v[100:103]
	v_mfma_f32_16x16x32_bf16 v[96:99], v[148:151], v[214:217], v[96:99]
	v_mfma_f32_16x16x32_bf16 v[92:95], v[140:143], v[222:225], v[92:95]
	s_mov_b32 m0, s46
	v_mfma_f32_16x16x32_bf16 v[88:91], v[148:151], v[222:225], v[88:91]
	global_load_lds_dwordx4 v[244:245], off
	v_mfma_f32_16x16x32_bf16 v[80:83], v[140:143], v[230:233], v[80:83]
	v_mfma_f32_16x16x32_bf16 v[72:75], v[148:151], v[230:233], v[72:75]
	v_mfma_f32_16x16x32_bf16 v[60:63], v[140:143], v[238:241], v[60:63]
	v_mfma_f32_16x16x32_bf16 v[56:59], v[148:151], v[238:241], v[56:59]
	s_setprio 0
	s_setprio 1
	v_mfma_f32_16x16x32_bf16 v[36:39], v[152:155], v[210:213], v[36:39]
	v_mfma_f32_16x16x32_bf16 v[32:35], v[190:193], v[210:213], v[32:35]
	v_mfma_f32_16x16x32_bf16 v[28:31], v[152:155], v[218:221], v[28:31]
	v_mfma_f32_16x16x32_bf16 v[24:27], v[190:193], v[218:221], v[24:27]
	v_mfma_f32_16x16x32_bf16 v[20:23], v[152:155], v[226:229], v[20:23]
	v_mfma_f32_16x16x32_bf16 v[16:19], v[190:193], v[226:229], v[16:19]
	v_mfma_f32_16x16x32_bf16 v[12:15], v[152:155], v[234:237], v[12:15]
	v_mfma_f32_16x16x32_bf16 v[8:11], v[190:193], v[234:237], v[8:11]
	s_barrier
; #define PG8_STAGE(bufoff, gbase, voff) do { _Pragma("unroll") for (int _i = 0; _i < 2; ++_i) \
;         __builtin_amdgcn_global_load_lds((const unsigned*)((const char*)(gbase) + (voff)[_i]), (PG8_LAS unsigned*)(lds + (bufoff) + ldsw + _i * 8192), 16, 0, 0); } while (0)
; #define PG8_LDA(dst, b, h) do { _Pragma("unroll") for (int m = 0; m < 4; ++m) _Pragma("unroll") for (int k = 0; k < 2; ++k) dst[m][k] = *(const PG8_LAS bf16x8*)(lds + PG8_SA(b, h) + aoff + m * 2048 + k * 1024); } while (0)
; #define PG8_LDB(dst, b, h) do { _Pragma("unroll") for (int n = 0; n < 2; ++n) _Pragma("unroll") for (int k = 0; k < 2; ++k) dst[n][k] = *(const PG8_LAS bf16x8*)(lds + PG8_SB(b, h) + boff + n * 2048 + k * 1024); } while (0)
; #define PG8_MMA(ai, bj, At, Bt) do { __builtin_amdgcn_s_setprio(1); _Pragma("unroll") for (int m = 0; m < 4; ++m) _Pragma("unroll") for (int n = 0; n < 2; ++n) _Pragma("unroll") for (int k = 0; k < 2; ++k) \
;         acc[ai][bj][m][n] = __builtin_amdgcn_mfma_f32_16x16x32_bf16(Bt[n][k], At[m][k], acc[ai][bj][m][n], 0, 0, 0); __builtin_amdgcn_s_setprio(0); } while (0)
; #define PG8_WAIT_V(n) asm volatile("s_waitcnt vmcnt(" #n ")" ::: "memory")
; #define PG8_WAIT_L(n) asm volatile("s_waitcnt lgkmcnt(" #n ")" ::: "memory")
; #define PG8_BAR __builtin_amdgcn_s_barrier()
; #define PG8_SCHED __builtin_amdgcn_sched_barrier(0)
; template <class Epi, class Sched, bool ALIGN_EPI = false, bool SP2 = false>
; __device__ __forceinline__ void gemm_phase(PG8_LAS unsigned char* lds, const Gemm g, const Sched& S, const Epi& E) {
;     ...
;             PG8_WAIT_V(8); PG8_WAIT_L(0); PG8_BAR; PG8_MMA(1, 0, At, B0); PG8_MMA(1, 1, At, B1); PG8_BAR; PG8_SCHED;
;             PG8_LDB(B0, 1, 0); PG8_LDB(B1, 1, 1); PG8_SCHED; PG8_LDA(At, 1, 0); PG8_STAGE(PG8_SA(0, 1), a2 + hstep, voffA);
;             PG8_WAIT_V(8); PG8_WAIT_L(0); PG8_BAR; PG8_MMA(0, 0, At, B0); PG8_MMA(0, 1, At, B1); PG8_BAR; PG8_SCHED;
	v_mfma_f32_16x16x32_bf16 v[36:39], v[186:189], v[214:217], v[36:39]
	v_mfma_f32_16x16x32_bf16 v[32:35], v[198:201], v[214:217], v[32:35]
	v_mfma_f32_16x16x32_bf16 v[28:31], v[186:189], v[222:225], v[28:31]
	v_mfma_f32_16x16x32_bf16 v[24:27], v[198:201], v[222:225], v[24:27]
	v_mfma_f32_16x16x32_bf16 v[20:23], v[186:189], v[230:233], v[20:23]
	v_mfma_f32_16x16x32_bf16 v[16:19], v[198:201], v[230:233], v[16:19]
	v_mfma_f32_16x16x32_bf16 v[12:15], v[186:189], v[238:241], v[12:15]
	v_mfma_f32_16x16x32_bf16 v[8:11], v[198:201], v[238:241], v[8:11]
	s_setprio 0
	s_add_i32 s18, 0, 0x18000
	v_add_u32_e32 v0, s18, v194
	ds_read_b128 v[136:139], v0
	ds_read_b128 v[140:143], v0 offset:1024
	ds_read_b128 v[144:147], v0 offset:2048
	ds_read_b128 v[148:151], v0 offset:3072
	v_add_u32_e32 v0, s33, v194
	ds_read_b128 v[152:155], v0
	ds_read_b128 v[186:189], v0 offset:1024
	ds_read_b128 v[190:193], v0 offset:2048
	ds_read_b128 v[198:201], v0 offset:3072
	s_add_u32 s16, s42, 0x40000
	s_addc_u32 s17, s43, 0
	s_mov_b32 m0, s47
	v_lshl_add_u64 v[246:247], s[16:17], 0, v[178:179]
	ds_read_b128 v[210:213], v196 offset:32768
	ds_read_b128 v[214:217], v196 offset:33792
	ds_read_b128 v[218:221], v196 offset:34816
	ds_read_b128 v[222:225], v196 offset:35840
	ds_read_b128 v[226:229], v196 offset:36864
	ds_read_b128 v[230:233], v196 offset:37888
	ds_read_b128 v[234:237], v196 offset:38912
	ds_read_b128 v[238:241], v196 offset:39936
	global_load_lds_dwordx4 v[246:247], off
	v_lshl_add_u64 v[246:247], s[16:17], 0, v[160:161]
	s_mov_b32 m0, s48
	s_nop 0
	global_load_lds_dwordx4 v[246:247], off
	s_waitcnt vmcnt(8)
	s_waitcnt lgkmcnt(0)
	s_barrier
	s_waitcnt lgkmcnt(0)
	v_mfma_f32_16x16x32_bf16 v[132:135], v[136:139], v[210:213], v[132:135]
	v_mfma_f32_16x16x32_bf16 v[128:131], v[144:147], v[210:213], v[128:131]
	v_mfma_f32_16x16x32_bf16 v[124:127], v[136:139], v[218:221], v[124:127]
	v_mfma_f32_16x16x32_bf16 v[120:123], v[144:147], v[218:221], v[120:123]
	v_mfma_f32_16x16x32_bf16 v[116:119], v[136:139], v[226:229], v[116:119]
	v_mfma_f32_16x16x32_bf16 v[112:115], v[144:147], v[226:229], v[112:115]
	v_mfma_f32_16x16x32_bf16 v[108:111], v[136:139], v[234:237], v[108:111]
	v_mfma_f32_16x16x32_bf16 v[104:107], v[144:147], v[234:237], v[104:107]
	s_setprio 1
	v_mfma_f32_16x16x32_bf16 v[132:135], v[140:143], v[214:217], v[132:135]
	v_mfma_f32_16x16x32_bf16 v[128:131], v[148:151], v[214:217], v[128:131]
	v_mfma_f32_16x16x32_bf16 v[124:127], v[140:143], v[222:225], v[124:127]
	v_mfma_f32_16x16x32_bf16 v[120:123], v[148:151], v[222:225], v[120:123]
	v_mfma_f32_16x16x32_bf16 v[116:119], v[140:143], v[230:233], v[116:119]
	v_mfma_f32_16x16x32_bf16 v[112:115], v[148:151], v[230:233], v[112:115]
	v_mfma_f32_16x16x32_bf16 v[108:111], v[140:143], v[238:241], v[108:111]
	v_mfma_f32_16x16x32_bf16 v[104:107], v[148:151], v[238:241], v[104:107]
	s_setprio 0
	s_setprio 1
	v_mfma_f32_16x16x32_bf16 v[84:87], v[152:155], v[210:213], v[84:87]
	v_mfma_f32_16x16x32_bf16 v[76:79], v[190:193], v[210:213], v[76:79]
	v_mfma_f32_16x16x32_bf16 v[68:71], v[152:155], v[218:221], v[68:71]
	v_mfma_f32_16x16x32_bf16 v[64:67], v[190:193], v[218:221], v[64:67]
	v_mfma_f32_16x16x32_bf16 v[52:55], v[152:155], v[226:229], v[52:55]
	v_mfma_f32_16x16x32_bf16 v[48:51], v[190:193], v[226:229], v[48:51]
	v_mfma_f32_16x16x32_bf16 v[44:47], v[152:155], v[234:237], v[44:47]
	v_mfma_f32_16x16x32_bf16 v[40:43], v[190:193], v[234:237], v[40:43]
	s_barrier
; #define PG8_STAGE(bufoff, gbase, voff) do { _Pragma("unroll") for (int _i = 0; _i < 2; ++_i) \
;         __builtin_amdgcn_global_load_lds((const unsigned*)((const char*)(gbase) + (voff)[_i]), (PG8_LAS unsigned*)(lds + (bufoff) + ldsw + _i * 8192), 16, 0, 0); } while (0)
; #define PG8_LDA(dst, b, h) do { _Pragma("unroll") for (int m = 0; m < 4; ++m) _Pragma("unroll") for (int k = 0; k < 2; ++k) dst[m][k] = *(const PG8_LAS bf16x8*)(lds + PG8_SA(b, h) + aoff + m * 2048 + k * 1024); } while (0)
; #define PG8_MMA(ai, bj, At, Bt) do { __builtin_amdgcn_s_setprio(1); _Pragma("unroll") for (int m = 0; m < 4; ++m) _Pragma("unroll") for (int n = 0; n < 2; ++n) _Pragma("unroll") for (int k = 0; k < 2; ++k) \
;         acc[ai][bj][m][n] = __builtin_amdgcn_mfma_f32_16x16x32_bf16(Bt[n][k], At[m][k], acc[ai][bj][m][n], 0, 0, 0); __builtin_amdgcn_s_setprio(0); } while (0)
; #define PG8_WAIT_V(n) asm volatile("s_waitcnt vmcnt(" #n ")" ::: "memory")
; #define PG8_WAIT_L(n) asm volatile("s_waitcnt lgkmcnt(" #n ")" ::: "memory")
; #define PG8_BAR __builtin_amdgcn_s_barrier()
; #define PG8_SCHED __builtin_amdgcn_sched_barrier(0)
; template <class Epi, class Sched, bool ALIGN_EPI = false, bool SP2 = false>
; __device__ __forceinline__ void gemm_phase(PG8_LAS unsigned char* lds, const Gemm g, const Sched& S, const Epi& E) {
;     ...
;             PG8_WAIT_V(8); PG8_WAIT_L(0); PG8_BAR; PG8_MMA(0, 0, At, B0); PG8_MMA(0, 1, At, B1); PG8_BAR; PG8_SCHED;
;             PG8_LDA(At, 1, 1); PG8_STAGE(PG8_SB(1, 0), b3, voffB); PG8_STAGE(PG8_SB(1, 1), b3 + hstep, voffB); PG8_STAGE(PG8_SA(1, 0), a3, voffA);
;             PG8_WAIT_V(8); PG8_WAIT_L(0); PG8_BAR; PG8_MMA(1, 0, At, B0); PG8_MMA(1, 1, At, B1); PG8_BAR; PG8_SCHED;
	v_mfma_f32_16x16x32_bf16 v[84:87], v[186:189], v[214:217], v[84:87]
	v_mfma_f32_16x16x32_bf16 v[76:79], v[198:201], v[214:217], v[76:79]
	v_mfma_f32_16x16x32_bf16 v[68:71], v[186:189], v[222:225], v[68:71]
	v_mfma_f32_16x16x32_bf16 v[64:67], v[198:201], v[222:225], v[64:67]
	v_mfma_f32_16x16x32_bf16 v[52:55], v[186:189], v[230:233], v[52:55]
	v_mfma_f32_16x16x32_bf16 v[48:51], v[198:201], v[230:233], v[48:51]
	v_mfma_f32_16x16x32_bf16 v[44:47], v[186:189], v[238:241], v[44:47]
	v_mfma_f32_16x16x32_bf16 v[40:43], v[198:201], v[238:241], v[40:43]
	s_setprio 0
	s_add_i32 s16, s18, s44
	v_lshl_add_u64 v[2:3], v[2:3], 0, s[20:21]
	s_mov_b32 m0, s16
	ds_read_b128 v[210:213], v196 offset:49152
	ds_read_b128 v[214:217], v196 offset:50176
	ds_read_b128 v[218:221], v196 offset:51200
	ds_read_b128 v[222:225], v196 offset:52224
	ds_read_b128 v[226:229], v196 offset:53248
	ds_read_b128 v[230:233], v196 offset:54272
	ds_read_b128 v[234:237], v196 offset:55296
	ds_read_b128 v[238:241], v196 offset:56320
	global_load_lds_dwordx4 v[2:3], off
	s_add_i32 m0, s16, 0x2000
	s_add_u32 s16, s40, 0x40080
	v_lshl_add_u64 v[2:3], v[156:157], 0, s[20:21]
	s_addc_u32 s17, s41, 0
	s_add_i32 s18, s33, s44
	global_load_lds_dwordx4 v[2:3], off
	v_lshl_add_u64 v[2:3], s[16:17], 0, v[162:163]
	s_mov_b32 m0, s18
	s_nop 0
	global_load_lds_dwordx4 v[2:3], off
	v_lshl_add_u64 v[2:3], s[16:17], 0, v[158:159]
	s_add_i32 m0, s18, 0x2000
	s_nop 0
	global_load_lds_dwordx4 v[2:3], off
	v_lshl_add_u64 v[2:3], v[242:243], 0, s[20:21]
	v_lshl_add_u64 v[244:245], v[244:245], 0, s[20:21]
	s_waitcnt vmcnt(6)
	s_waitcnt lgkmcnt(0)
	s_barrier
	s_waitcnt lgkmcnt(0)
	v_mfma_f32_16x16x32_bf16 v[100:103], v[136:139], v[210:213], v[100:103]
	v_mfma_f32_16x16x32_bf16 v[96:99], v[144:147], v[210:213], v[96:99]
	v_mfma_f32_16x16x32_bf16 v[92:95], v[136:139], v[218:221], v[92:95]
	s_mov_b32 m0, s49
	v_mfma_f32_16x16x32_bf16 v[88:91], v[144:147], v[218:221], v[88:91]
	global_load_lds_dwordx4 v[2:3], off
	v_mfma_f32_16x16x32_bf16 v[80:83], v[136:139], v[226:229], v[80:83]
	v_mfma_f32_16x16x32_bf16 v[72:75], v[144:147], v[226:229], v[72:75]
	v_mfma_f32_16x16x32_bf16 v[60:63], v[136:139], v[234:237], v[60:63]
	v_mfma_f32_16x16x32_bf16 v[56:59], v[144:147], v[234:237], v[56:59]
	s_setprio 1
	v_mfma_f32_16x16x32_bf16 v[100:103], v[140:143], v[214:217], v[100:103]
	v_mfma_f32_16x16x32_bf16 v[96:99], v[148:151], v[214:217], v[96:99]
	v_mfma_f32_16x16x32_bf16 v[92:95], v[140:143], v[222:225], v[92:95]
	s_mov_b32 m0, s50
	v_mfma_f32_16x16x32_bf16 v[88:91], v[148:151], v[222:225], v[88:91]
	global_load_lds_dwordx4 v[244:245], off
	v_mfma_f32_16x16x32_bf16 v[80:83], v[140:143], v[230:233], v[80:83]
	v_mfma_f32_16x16x32_bf16 v[72:75], v[148:151], v[230:233], v[72:75]
	v_mfma_f32_16x16x32_bf16 v[60:63], v[140:143], v[238:241], v[60:63]
	v_mfma_f32_16x16x32_bf16 v[56:59], v[148:151], v[238:241], v[56:59]
	s_setprio 0
	s_setprio 1
	v_mfma_f32_16x16x32_bf16 v[36:39], v[152:155], v[210:213], v[36:39]
	v_mfma_f32_16x16x32_bf16 v[32:35], v[190:193], v[210:213], v[32:35]
	v_mfma_f32_16x16x32_bf16 v[28:31], v[152:155], v[218:221], v[28:31]
	v_mfma_f32_16x16x32_bf16 v[24:27], v[190:193], v[218:221], v[24:27]
	v_mfma_f32_16x16x32_bf16 v[20:23], v[152:155], v[226:229], v[20:23]
	v_mfma_f32_16x16x32_bf16 v[16:19], v[190:193], v[226:229], v[16:19]
	v_mfma_f32_16x16x32_bf16 v[12:15], v[152:155], v[234:237], v[12:15]
	v_mfma_f32_16x16x32_bf16 v[8:11], v[190:193], v[234:237], v[8:11]
	s_barrier
	v_mfma_f32_16x16x32_bf16 v[36:39], v[186:189], v[214:217], v[36:39]
	v_mfma_f32_16x16x32_bf16 v[32:35], v[198:201], v[214:217], v[32:35]
	v_mfma_f32_16x16x32_bf16 v[28:31], v[186:189], v[222:225], v[28:31]
	v_mfma_f32_16x16x32_bf16 v[24:27], v[198:201], v[222:225], v[24:27]
	v_mfma_f32_16x16x32_bf16 v[20:23], v[186:189], v[230:233], v[20:23]
	v_mfma_f32_16x16x32_bf16 v[16:19], v[198:201], v[230:233], v[16:19]
	v_mfma_f32_16x16x32_bf16 v[12:15], v[186:189], v[238:241], v[12:15]
	v_mfma_f32_16x16x32_bf16 v[8:11], v[198:201], v[238:241], v[8:11]
	s_setprio 0
	s_add_i32 s55, s55, 2
	s_add_u32 s8, s8, 0x100
	s_addc_u32 s9, s9, 0
	s_add_u32 s53, s53, 0x100
	s_addc_u32 s54, s54, 0
	s_cmp_gt_u32 s55, 13
	s_cbranch_scc0 .LBB0_165
	s_and_b64 vcc, exec, s[10:11]
	s_cbranch_vccz .LBB0_168
	s_barrier
	s_setprio 1

; #define PG8_STAGE(bufoff, gbase, voff) do { _Pragma("unroll") for (int _i = 0; _i < 2; ++_i) \
;         __builtin_amdgcn_global_load_lds((const unsigned*)((const char*)(gbase) + (voff)[_i]), (PG8_LAS unsigned*)(lds + (bufoff) + ldsw + _i * 8192), 16, 0, 0); } while (0)
; #define PG8_LDA(dst, b, h) do { _Pragma("unroll") for (int m = 0; m < 4; ++m) _Pragma("unroll") for (int k = 0; k < 2; ++k) dst[m][k] = *(const PG8_LAS bf16x8*)(lds + PG8_SA(b, h) + aoff + m * 2048 + k * 1024); } while (0)
; #define PG8_LDB(dst, b, h) do { _Pragma("unroll") for (int n = 0; n < 2; ++n) _Pragma("unroll") for (int k = 0; k < 2; ++k) dst[n][k] = *(const PG8_LAS bf16x8*)(lds + PG8_SB(b, h) + boff + n * 2048 + k * 1024); } while (0)
; #define PG8_WAIT_V(n) asm volatile("s_waitcnt vmcnt(" #n ")" ::: "memory")
; #define PG8_WAIT_L(n) asm volatile("s_waitcnt lgkmcnt(" #n ")" ::: "memory")
; #define PG8_BAR __builtin_amdgcn_s_barrier()
; #define PG8_SCHED __builtin_amdgcn_sched_barrier(0)
; template <class Epi, class Sched, bool ALIGN_EPI = false, bool SP2 = false>
; __device__ __forceinline__ void gemm_phase(PG8_LAS unsigned char* lds, const Gemm g, const Sched& S, const Epi& E) {
;     ...
;         const char* nA = has_next ? (const char*)g.A + (size_t)nxt.pm * tstep : cA; const char* nB = has_next ? (const char*)g.Bt + (size_t)nxt.pn * tstep : cB;
;         for (int t = 0; t < nt; t += 2) {
;             const bool last = (t == nt - 2);
;             const char* a1 = cA + (size_t)(t + 1) * kstep;
;             const char* a2 = last ? nA : cA + (size_t)(t + 2) * kstep; const char* b2 = last ? nB : cB + (size_t)(t + 2) * kstep;
;             const char* a3 = a2 + kstep; const char* b3 = b2 + kstep;
;             if (last && has_next) S.a_ready(nxt);
;             if constexpr (SP2) {
;             PG8_LDB(B0, 0, 0); PG8_LDB(B1, 0, 1); PG8_SCHED; PG8_LDA(At, 0, 0); PG8_STAGE(PG8_SA(1, 1), a1 + hstep, voffA);
;             PG8_WAIT_V(8); PG8_WAIT_L(0); PG8_BAR; PG8_MMA(0, 0, At, B0); PG8_MMA(0, 1, At, B1); PG8_BAR; PG8_SCHED;
;             PG8_LDA(At, 0, 1); PG8_STAGE(PG8_SB(0, 0), b2, voffB); PG8_STAGE(PG8_SB(0, 1), b2 + hstep, voffB); PG8_STAGE(PG8_SA(0, 0), a2, voffA);
;             PG8_WAIT_V(8); PG8_WAIT_L(0); PG8_BAR; PG8_MMA(1, 0, At, B0); PG8_MMA(1, 1, At, B1); PG8_BAR; PG8_SCHED;
.LBB0_203:
	s_add_i32 s36, s28, 2
	s_add_u32 s16, s24, 0x80
	s_addc_u32 s17, s25, 0
	s_add_i32 s18, 0, 0x10000
	s_cmp_eq_u32 s60, s28
	s_cselect_b32 s29, s3, s17
	s_cselect_b32 s28, s2, s16
	v_add_u32_e32 v137, s18, v200
	s_cselect_b32 s17, s9, s35
	s_cselect_b32 s16, s8, s23
	s_add_i32 s19, 0, 0x14000
	ds_read_b128 v[144:147], v137
	ds_read_b128 v[148:151], v137 offset:1024
	ds_read_b128 v[152:155], v137 offset:2048
	ds_read_b128 v[156:159], v137 offset:3072
	v_add_u32_e32 v137, s19, v200
	ds_read_b128 v[160:163], v137
	ds_read_b128 v[178:181], v137 offset:1024
	ds_read_b128 v[182:185], v137 offset:2048
	ds_read_b128 v[186:189], v137 offset:3072
	v_lshl_add_u64 v[198:199], s[24:25], 0, v[140:141]
	s_add_i32 m0, s52, 0xc000
	ds_read_b128 v[190:193], v210
	ds_read_b128 v[194:197], v210 offset:1024
	ds_read_b128 v[212:215], v210 offset:2048
	ds_read_b128 v[216:219], v210 offset:3072
	ds_read_b128 v[220:223], v210 offset:4096
	ds_read_b128 v[224:227], v210 offset:5120
	ds_read_b128 v[228:231], v210 offset:6144
	ds_read_b128 v[232:235], v210 offset:7168
	global_load_lds_dwordx4 v[198:199], off
	v_lshl_add_u64 v[198:199], s[24:25], 0, v[142:143]
	s_add_i32 m0, s52, 0xe000
	s_nop 0
	global_load_lds_dwordx4 v[198:199], off
	s_waitcnt vmcnt(8)
	s_waitcnt lgkmcnt(0)
	s_barrier
	s_waitcnt lgkmcnt(0)
	v_mfma_f32_16x16x32_bf16 v[132:135], v[144:147], v[190:193], v[132:135]
	v_mfma_f32_16x16x32_bf16 v[128:131], v[152:155], v[190:193], v[128:131]
	v_mfma_f32_16x16x32_bf16 v[116:119], v[144:147], v[212:215], v[116:119]
	v_mfma_f32_16x16x32_bf16 v[112:115], v[152:155], v[212:215], v[112:115]
	v_mfma_f32_16x16x32_bf16 v[100:103], v[144:147], v[220:223], v[100:103]
	v_mfma_f32_16x16x32_bf16 v[96:99], v[152:155], v[220:223], v[96:99]
	v_mfma_f32_16x16x32_bf16 v[84:87], v[144:147], v[228:231], v[84:87]
	v_mfma_f32_16x16x32_bf16 v[80:83], v[152:155], v[228:231], v[80:83]
	s_setprio 1
	v_mfma_f32_16x16x32_bf16 v[132:135], v[148:151], v[194:197], v[132:135]
	v_mfma_f32_16x16x32_bf16 v[128:131], v[156:159], v[194:197], v[128:131]
	v_mfma_f32_16x16x32_bf16 v[116:119], v[148:151], v[216:219], v[116:119]
	v_mfma_f32_16x16x32_bf16 v[112:115], v[156:159], v[216:219], v[112:115]
	v_mfma_f32_16x16x32_bf16 v[100:103], v[148:151], v[224:227], v[100:103]
	v_mfma_f32_16x16x32_bf16 v[96:99], v[156:159], v[224:227], v[96:99]
	v_mfma_f32_16x16x32_bf16 v[84:87], v[148:151], v[232:235], v[84:87]
	v_mfma_f32_16x16x32_bf16 v[80:83], v[156:159], v[232:235], v[80:83]
	s_setprio 0
	s_setprio 1
	v_mfma_f32_16x16x32_bf16 v[124:127], v[160:163], v[190:193], v[124:127]
	v_mfma_f32_16x16x32_bf16 v[120:123], v[182:185], v[190:193], v[120:123]
	v_mfma_f32_16x16x32_bf16 v[108:111], v[160:163], v[212:215], v[108:111]
	v_mfma_f32_16x16x32_bf16 v[104:107], v[182:185], v[212:215], v[104:107]
	v_mfma_f32_16x16x32_bf16 v[92:95], v[160:163], v[220:223], v[92:95]
	v_mfma_f32_16x16x32_bf16 v[88:91], v[182:185], v[220:223], v[88:91]
	v_mfma_f32_16x16x32_bf16 v[76:79], v[160:163], v[228:231], v[76:79]
	v_mfma_f32_16x16x32_bf16 v[72:75], v[182:185], v[228:231], v[72:75]
	s_barrier
	v_mfma_f32_16x16x32_bf16 v[124:127], v[178:181], v[194:197], v[124:127]
	v_mfma_f32_16x16x32_bf16 v[120:123], v[186:189], v[194:197], v[120:123]
	v_mfma_f32_16x16x32_bf16 v[108:111], v[178:181], v[216:219], v[108:111]
	v_mfma_f32_16x16x32_bf16 v[104:107], v[186:189], v[216:219], v[104:107]
	v_mfma_f32_16x16x32_bf16 v[92:95], v[178:181], v[224:227], v[92:95]
	v_mfma_f32_16x16x32_bf16 v[88:91], v[186:189], v[224:227], v[88:91]
	v_mfma_f32_16x16x32_bf16 v[76:79], v[178:181], v[232:235], v[76:79]
	v_mfma_f32_16x16x32_bf16 v[72:75], v[186:189], v[232:235], v[72:75]
	s_setprio 0
	s_add_i32 s18, s18, s41
	v_lshl_add_u64 v[198:199], s[16:17], 0, v[0:1]
	s_mov_b32 m0, s18
	ds_read_b128 v[190:193], v210 offset:16384
	ds_read_b128 v[194:197], v210 offset:17408
	ds_read_b128 v[212:215], v210 offset:18432
	ds_read_b128 v[216:219], v210 offset:19456
	ds_read_b128 v[220:223], v210 offset:20480
	ds_read_b128 v[224:227], v210 offset:21504
	ds_read_b128 v[228:231], v210 offset:22528
	ds_read_b128 v[232:235], v210 offset:23552
	global_load_lds_dwordx4 v[198:199], off
	s_add_i32 m0, s18, 0x2000
	v_lshl_add_u64 v[236:237], s[16:17], 0, v[2:3]
	s_add_u32 s16, s16, s12
	s_addc_u32 s17, s17, 0
	s_add_i32 s18, s19, s41
	global_load_lds_dwordx4 v[236:237], off
	v_lshl_add_u64 v[238:239], s[16:17], 0, v[0:1]
	s_mov_b32 m0, s18
	v_lshl_add_u64 v[240:241], s[16:17], 0, v[2:3]
	global_load_lds_dwordx4 v[238:239], off
	s_add_i32 m0, s18, 0x2000
	v_lshl_add_u64 v[242:243], s[28:29], 0, v[0:1]
	global_load_lds_dwordx4 v[240:241], off
	v_lshl_add_u64 v[244:245], s[28:29], 0, v[2:3]
	s_waitcnt vmcnt(6)
	s_waitcnt lgkmcnt(0)
	s_barrier
	s_waitcnt lgkmcnt(0)
	v_mfma_f32_16x16x32_bf16 v[68:71], v[144:147], v[190:193], v[68:71]
	v_mfma_f32_16x16x32_bf16 v[64:67], v[152:155], v[190:193], v[64:67]
	v_mfma_f32_16x16x32_bf16 v[52:55], v[144:147], v[212:215], v[52:55]
	s_mov_b32 m0, s52
	v_mfma_f32_16x16x32_bf16 v[48:51], v[152:155], v[212:215], v[48:51]
	global_load_lds_dwordx4 v[242:243], off
	v_mfma_f32_16x16x32_bf16 v[36:39], v[144:147], v[220:223], v[36:39]
	v_mfma_f32_16x16x32_bf16 v[32:35], v[152:155], v[220:223], v[32:35]
	v_mfma_f32_16x16x32_bf16 v[20:23], v[144:147], v[228:231], v[20:23]
	v_mfma_f32_16x16x32_bf16 v[16:19], v[152:155], v[228:231], v[16:19]
	s_setprio 1
	v_mfma_f32_16x16x32_bf16 v[68:71], v[148:151], v[194:197], v[68:71]
	v_mfma_f32_16x16x32_bf16 v[64:67], v[156:159], v[194:197], v[64:67]
	v_mfma_f32_16x16x32_bf16 v[52:55], v[148:151], v[216:219], v[52:55]
	s_mov_b32 m0, s53
	v_mfma_f32_16x16x32_bf16 v[48:51], v[156:159], v[216:219], v[48:51]
	global_load_lds_dwordx4 v[244:245], off
	v_mfma_f32_16x16x32_bf16 v[36:39], v[148:151], v[224:227], v[36:39]
	v_mfma_f32_16x16x32_bf16 v[32:35], v[156:159], v[224:227], v[32:35]
	v_mfma_f32_16x16x32_bf16 v[20:23], v[148:151], v[232:235], v[20:23]
	v_mfma_f32_16x16x32_bf16 v[16:19], v[156:159], v[232:235], v[16:19]
	s_setprio 0
	s_setprio 1
	v_mfma_f32_16x16x32_bf16 v[60:63], v[160:163], v[190:193], v[60:63]
	v_mfma_f32_16x16x32_bf16 v[56:59], v[182:185], v[190:193], v[56:59]
	v_mfma_f32_16x16x32_bf16 v[44:47], v[160:163], v[212:215], v[44:47]
	v_mfma_f32_16x16x32_bf16 v[40:43], v[182:185], v[212:215], v[40:43]
	v_mfma_f32_16x16x32_bf16 v[28:31], v[160:163], v[220:223], v[28:31]
	v_mfma_f32_16x16x32_bf16 v[24:27], v[182:185], v[220:223], v[24:27]
	v_mfma_f32_16x16x32_bf16 v[12:15], v[160:163], v[228:231], v[12:15]
	v_mfma_f32_16x16x32_bf16 v[8:11], v[182:185], v[228:231], v[8:11]
	s_barrier
; #define PG8_STAGE(bufoff, gbase, voff) do { _Pragma("unroll") for (int _i = 0; _i < 2; ++_i) \
;         __builtin_amdgcn_global_load_lds((const unsigned*)((const char*)(gbase) + (voff)[_i]), (PG8_LAS unsigned*)(lds + (bufoff) + ldsw + _i * 8192), 16, 0, 0); } while (0)
; #define PG8_LDA(dst, b, h) do { _Pragma("unroll") for (int m = 0; m < 4; ++m) _Pragma("unroll") for (int k = 0; k < 2; ++k) dst[m][k] = *(const PG8_LAS bf16x8*)(lds + PG8_SA(b, h) + aoff + m * 2048 + k * 1024); } while (0)
; #define PG8_LDB(dst, b, h) do { _Pragma("unroll") for (int n = 0; n < 2; ++n) _Pragma("unroll") for (int k = 0; k < 2; ++k) dst[n][k] = *(const PG8_LAS bf16x8*)(lds + PG8_SB(b, h) + boff + n * 2048 + k * 1024); } while (0)
; #define PG8_MMA(ai, bj, At, Bt) do { __builtin_amdgcn_s_setprio(1); _Pragma("unroll") for (int m = 0; m < 4; ++m) _Pragma("unroll") for (int n = 0; n < 2; ++n) _Pragma("unroll") for (int k = 0; k < 2; ++k) \
;         acc[ai][bj][m][n] = __builtin_amdgcn_mfma_f32_16x16x32_bf16(Bt[n][k], At[m][k], acc[ai][bj][m][n], 0, 0, 0); __builtin_amdgcn_s_setprio(0); } while (0)
; #define PG8_WAIT_V(n) asm volatile("s_waitcnt vmcnt(" #n ")" ::: "memory")
; #define PG8_WAIT_L(n) asm volatile("s_waitcnt lgkmcnt(" #n ")" ::: "memory")
; #define PG8_BAR __builtin_amdgcn_s_barrier()
; #define PG8_SCHED __builtin_amdgcn_sched_barrier(0)
; template <class Epi, class Sched, bool ALIGN_EPI = false, bool SP2 = false>
; __device__ __forceinline__ void gemm_phase(PG8_LAS unsigned char* lds, const Gemm g, const Sched& S, const Epi& E) {
;     ...
;             PG8_WAIT_V(8); PG8_WAIT_L(0); PG8_BAR; PG8_MMA(1, 0, At, B0); PG8_MMA(1, 1, At, B1); PG8_BAR; PG8_SCHED;
;             PG8_LDB(B0, 1, 0); PG8_LDB(B1, 1, 1); PG8_SCHED; PG8_LDA(At, 1, 0); PG8_STAGE(PG8_SA(0, 1), a2 + hstep, voffA);
;             PG8_WAIT_V(8); PG8_WAIT_L(0); PG8_BAR; PG8_MMA(0, 0, At, B0); PG8_MMA(0, 1, At, B1); PG8_BAR; PG8_SCHED;
	v_mfma_f32_16x16x32_bf16 v[60:63], v[178:181], v[194:197], v[60:63]
	v_mfma_f32_16x16x32_bf16 v[56:59], v[186:189], v[194:197], v[56:59]
	v_mfma_f32_16x16x32_bf16 v[44:47], v[178:181], v[216:219], v[44:47]
	v_mfma_f32_16x16x32_bf16 v[40:43], v[186:189], v[216:219], v[40:43]
	v_mfma_f32_16x16x32_bf16 v[28:31], v[178:181], v[224:227], v[28:31]
	v_mfma_f32_16x16x32_bf16 v[24:27], v[186:189], v[224:227], v[24:27]
	v_mfma_f32_16x16x32_bf16 v[12:15], v[178:181], v[232:235], v[12:15]
	v_mfma_f32_16x16x32_bf16 v[8:11], v[186:189], v[232:235], v[8:11]
	s_setprio 0
	s_add_i32 s18, 0, 0x18000
	v_add_u32_e32 v137, s18, v200
	ds_read_b128 v[144:147], v137
	ds_read_b128 v[148:151], v137 offset:1024
	ds_read_b128 v[152:155], v137 offset:2048
	ds_read_b128 v[156:159], v137 offset:3072
	v_add_u32_e32 v137, s33, v200
	ds_read_b128 v[160:163], v137
	ds_read_b128 v[178:181], v137 offset:1024
	ds_read_b128 v[182:185], v137 offset:2048
	ds_read_b128 v[186:189], v137 offset:3072
	s_add_u32 s16, s28, s12
	s_addc_u32 s17, s29, 0
	s_mov_b32 m0, s54
	v_lshl_add_u64 v[246:247], s[16:17], 0, v[0:1]
	ds_read_b128 v[190:193], v210 offset:32768
	ds_read_b128 v[194:197], v210 offset:33792
	ds_read_b128 v[212:215], v210 offset:34816
	ds_read_b128 v[216:219], v210 offset:35840
	ds_read_b128 v[220:223], v210 offset:36864
	ds_read_b128 v[224:227], v210 offset:37888
	ds_read_b128 v[228:231], v210 offset:38912
	ds_read_b128 v[232:235], v210 offset:39936
	global_load_lds_dwordx4 v[246:247], off
	v_lshl_add_u64 v[246:247], s[16:17], 0, v[2:3]
	s_mov_b32 m0, s55
	s_nop 0
	global_load_lds_dwordx4 v[246:247], off
	s_waitcnt vmcnt(8)
	s_waitcnt lgkmcnt(0)
	s_barrier
	s_waitcnt lgkmcnt(0)
	v_mfma_f32_16x16x32_bf16 v[132:135], v[144:147], v[190:193], v[132:135]
	v_mfma_f32_16x16x32_bf16 v[128:131], v[152:155], v[190:193], v[128:131]
	v_mfma_f32_16x16x32_bf16 v[116:119], v[144:147], v[212:215], v[116:119]
	v_mfma_f32_16x16x32_bf16 v[112:115], v[152:155], v[212:215], v[112:115]
	v_mfma_f32_16x16x32_bf16 v[100:103], v[144:147], v[220:223], v[100:103]
	v_mfma_f32_16x16x32_bf16 v[96:99], v[152:155], v[220:223], v[96:99]
	v_mfma_f32_16x16x32_bf16 v[84:87], v[144:147], v[228:231], v[84:87]
	v_mfma_f32_16x16x32_bf16 v[80:83], v[152:155], v[228:231], v[80:83]
	s_setprio 1
	v_mfma_f32_16x16x32_bf16 v[132:135], v[148:151], v[194:197], v[132:135]
	v_mfma_f32_16x16x32_bf16 v[128:131], v[156:159], v[194:197], v[128:131]
	v_mfma_f32_16x16x32_bf16 v[116:119], v[148:151], v[216:219], v[116:119]
	v_mfma_f32_16x16x32_bf16 v[112:115], v[156:159], v[216:219], v[112:115]
	v_mfma_f32_16x16x32_bf16 v[100:103], v[148:151], v[224:227], v[100:103]
	v_mfma_f32_16x16x32_bf16 v[96:99], v[156:159], v[224:227], v[96:99]
	v_mfma_f32_16x16x32_bf16 v[84:87], v[148:151], v[232:235], v[84:87]
	v_mfma_f32_16x16x32_bf16 v[80:83], v[156:159], v[232:235], v[80:83]
	s_setprio 0
	s_setprio 1
	v_mfma_f32_16x16x32_bf16 v[124:127], v[160:163], v[190:193], v[124:127]
	v_mfma_f32_16x16x32_bf16 v[120:123], v[182:185], v[190:193], v[120:123]
	v_mfma_f32_16x16x32_bf16 v[108:111], v[160:163], v[212:215], v[108:111]
	v_mfma_f32_16x16x32_bf16 v[104:107], v[182:185], v[212:215], v[104:107]
	v_mfma_f32_16x16x32_bf16 v[92:95], v[160:163], v[220:223], v[92:95]
	v_mfma_f32_16x16x32_bf16 v[88:91], v[182:185], v[220:223], v[88:91]
	v_mfma_f32_16x16x32_bf16 v[76:79], v[160:163], v[228:231], v[76:79]
	v_mfma_f32_16x16x32_bf16 v[72:75], v[182:185], v[228:231], v[72:75]
	s_barrier
; #define PG8_STAGE(bufoff, gbase, voff) do { _Pragma("unroll") for (int _i = 0; _i < 2; ++_i) \
;         __builtin_amdgcn_global_load_lds((const unsigned*)((const char*)(gbase) + (voff)[_i]), (PG8_LAS unsigned*)(lds + (bufoff) + ldsw + _i * 8192), 16, 0, 0); } while (0)
; #define PG8_LDA(dst, b, h) do { _Pragma("unroll") for (int m = 0; m < 4; ++m) _Pragma("unroll") for (int k = 0; k < 2; ++k) dst[m][k] = *(const PG8_LAS bf16x8*)(lds + PG8_SA(b, h) + aoff + m * 2048 + k * 1024); } while (0)
; #define PG8_MMA(ai, bj, At, Bt) do { __builtin_amdgcn_s_setprio(1); _Pragma("unroll") for (int m = 0; m < 4; ++m) _Pragma("unroll") for (int n = 0; n < 2; ++n) _Pragma("unroll") for (int k = 0; k < 2; ++k) \
;         acc[ai][bj][m][n] = __builtin_amdgcn_mfma_f32_16x16x32_bf16(Bt[n][k], At[m][k], acc[ai][bj][m][n], 0, 0, 0); __builtin_amdgcn_s_setprio(0); } while (0)
; #define PG8_WAIT_V(n) asm volatile("s_waitcnt vmcnt(" #n ")" ::: "memory")
; #define PG8_WAIT_L(n) asm volatile("s_waitcnt lgkmcnt(" #n ")" ::: "memory")
; #define PG8_BAR __builtin_amdgcn_s_barrier()
; #define PG8_SCHED __builtin_amdgcn_sched_barrier(0)
; template <class Epi, class Sched, bool ALIGN_EPI = false, bool SP2 = false>
; __device__ __forceinline__ void gemm_phase(PG8_LAS unsigned char* lds, const Gemm g, const Sched& S, const Epi& E) {
;     ...
;             PG8_WAIT_V(8); PG8_WAIT_L(0); PG8_BAR; PG8_MMA(0, 0, At, B0); PG8_MMA(0, 1, At, B1); PG8_BAR; PG8_SCHED;
;             PG8_LDA(At, 1, 1); PG8_STAGE(PG8_SB(1, 0), b3, voffB); PG8_STAGE(PG8_SB(1, 1), b3 + hstep, voffB); PG8_STAGE(PG8_SA(1, 0), a3, voffA);
;             PG8_WAIT_V(8); PG8_WAIT_L(0); PG8_BAR; PG8_MMA(1, 0, At, B0); PG8_MMA(1, 1, At, B1); PG8_BAR; PG8_SCHED;
	v_mfma_f32_16x16x32_bf16 v[124:127], v[178:181], v[194:197], v[124:127]
	v_mfma_f32_16x16x32_bf16 v[120:123], v[186:189], v[194:197], v[120:123]
	v_mfma_f32_16x16x32_bf16 v[108:111], v[178:181], v[216:219], v[108:111]
	v_mfma_f32_16x16x32_bf16 v[104:107], v[186:189], v[216:219], v[104:107]
	v_mfma_f32_16x16x32_bf16 v[92:95], v[178:181], v[224:227], v[92:95]
	v_mfma_f32_16x16x32_bf16 v[88:91], v[186:189], v[224:227], v[88:91]
	v_mfma_f32_16x16x32_bf16 v[76:79], v[178:181], v[232:235], v[76:79]
	v_mfma_f32_16x16x32_bf16 v[72:75], v[186:189], v[232:235], v[72:75]
	s_setprio 0
	s_add_i32 s16, s18, s41
	v_lshl_add_u64 v[198:199], v[198:199], 0, s[20:21]
	s_mov_b32 m0, s16
	ds_read_b128 v[190:193], v210 offset:49152
	ds_read_b128 v[194:197], v210 offset:50176
	ds_read_b128 v[212:215], v210 offset:51200
	ds_read_b128 v[216:219], v210 offset:52224
	ds_read_b128 v[220:223], v210 offset:53248
	ds_read_b128 v[224:227], v210 offset:54272
	ds_read_b128 v[228:231], v210 offset:55296
	ds_read_b128 v[232:235], v210 offset:56320
	global_load_lds_dwordx4 v[198:199], off
	v_lshl_add_u64 v[198:199], v[236:237], 0, s[20:21]
	s_add_i32 m0, s16, 0x2000
	s_add_i32 s16, s33, s41
	global_load_lds_dwordx4 v[198:199], off
	v_lshl_add_u64 v[198:199], v[238:239], 0, s[20:21]
	s_mov_b32 m0, s16
	s_nop 0
	global_load_lds_dwordx4 v[198:199], off
	v_lshl_add_u64 v[198:199], v[240:241], 0, s[20:21]
	s_add_i32 m0, s16, 0x2000
	s_nop 0
	global_load_lds_dwordx4 v[198:199], off
	v_lshl_add_u64 v[198:199], v[242:243], 0, s[20:21]
	v_lshl_add_u64 v[244:245], v[244:245], 0, s[20:21]
	s_waitcnt vmcnt(6)
	s_waitcnt lgkmcnt(0)
	s_barrier
	s_waitcnt lgkmcnt(0)
	v_mfma_f32_16x16x32_bf16 v[68:71], v[144:147], v[190:193], v[68:71]
	v_mfma_f32_16x16x32_bf16 v[64:67], v[152:155], v[190:193], v[64:67]
	v_mfma_f32_16x16x32_bf16 v[52:55], v[144:147], v[212:215], v[52:55]
	s_mov_b32 m0, s56
	v_mfma_f32_16x16x32_bf16 v[48:51], v[152:155], v[212:215], v[48:51]
	global_load_lds_dwordx4 v[198:199], off
	v_mfma_f32_16x16x32_bf16 v[36:39], v[144:147], v[220:223], v[36:39]
	v_mfma_f32_16x16x32_bf16 v[32:35], v[152:155], v[220:223], v[32:35]
	v_mfma_f32_16x16x32_bf16 v[20:23], v[144:147], v[228:231], v[20:23]
	v_mfma_f32_16x16x32_bf16 v[16:19], v[152:155], v[228:231], v[16:19]
	s_setprio 1
	v_mfma_f32_16x16x32_bf16 v[68:71], v[148:151], v[194:197], v[68:71]
	v_mfma_f32_16x16x32_bf16 v[64:67], v[156:159], v[194:197], v[64:67]
	v_mfma_f32_16x16x32_bf16 v[52:55], v[148:151], v[216:219], v[52:55]
	s_mov_b32 m0, s57
	v_mfma_f32_16x16x32_bf16 v[48:51], v[156:159], v[216:219], v[48:51]
	global_load_lds_dwordx4 v[244:245], off
	v_mfma_f32_16x16x32_bf16 v[36:39], v[148:151], v[224:227], v[36:39]
	v_mfma_f32_16x16x32_bf16 v[32:35], v[156:159], v[224:227], v[32:35]
	v_mfma_f32_16x16x32_bf16 v[20:23], v[148:151], v[232:235], v[20:23]
	v_mfma_f32_16x16x32_bf16 v[16:19], v[156:159], v[232:235], v[16:19]
	s_setprio 0
	s_setprio 1
	v_mfma_f32_16x16x32_bf16 v[60:63], v[160:163], v[190:193], v[60:63]
	v_mfma_f32_16x16x32_bf16 v[56:59], v[182:185], v[190:193], v[56:59]
	v_mfma_f32_16x16x32_bf16 v[44:47], v[160:163], v[212:215], v[44:47]
	v_mfma_f32_16x16x32_bf16 v[40:43], v[182:185], v[212:215], v[40:43]
	v_mfma_f32_16x16x32_bf16 v[28:31], v[160:163], v[220:223], v[28:31]
	v_mfma_f32_16x16x32_bf16 v[24:27], v[182:185], v[220:223], v[24:27]
	v_mfma_f32_16x16x32_bf16 v[12:15], v[160:163], v[228:231], v[12:15]
	v_mfma_f32_16x16x32_bf16 v[8:11], v[182:185], v[228:231], v[8:11]
	s_barrier
	v_mfma_f32_16x16x32_bf16 v[60:63], v[178:181], v[194:197], v[60:63]
	v_mfma_f32_16x16x32_bf16 v[56:59], v[186:189], v[194:197], v[56:59]
	v_mfma_f32_16x16x32_bf16 v[44:47], v[178:181], v[216:219], v[44:47]
	v_mfma_f32_16x16x32_bf16 v[40:43], v[186:189], v[216:219], v[40:43]
	v_mfma_f32_16x16x32_bf16 v[28:31], v[178:181], v[224:227], v[28:31]
	v_mfma_f32_16x16x32_bf16 v[24:27], v[186:189], v[224:227], v[24:27]
	v_mfma_f32_16x16x32_bf16 v[12:15], v[178:181], v[232:235], v[12:15]
	v_mfma_f32_16x16x32_bf16 v[8:11], v[186:189], v[232:235], v[8:11]
	s_setprio 0
	s_add_u32 s24, s24, 0x100
	s_addc_u32 s25, s25, 0
	s_add_u32 s23, s23, 0x100
	s_addc_u32 s35, s35, 0
	s_cmp_ge_u32 s36, s59
	s_mov_b32 s28, s36
	s_cbranch_scc0 .LBB0_203
	s_and_b64 vcc, exec, s[46:47]
	s_cbranch_vccz .LBB0_206
	s_barrier
	s_setprio 1

; #define PG8_STAGE(bufoff, gbase, voff) do { _Pragma("unroll") for (int _i = 0; _i < 2; ++_i) \
;         __builtin_amdgcn_global_load_lds((const unsigned*)((const char*)(gbase) + (voff)[_i]), (PG8_LAS unsigned*)(lds + (bufoff) + ldsw + _i * 8192), 16, 0, 0); } while (0)
; #define PG8_LDA(dst, b, h) do { _Pragma("unroll") for (int m = 0; m < 4; ++m) _Pragma("unroll") for (int k = 0; k < 2; ++k) dst[m][k] = *(const PG8_LAS bf16x8*)(lds + PG8_SA(b, h) + aoff + m * 2048 + k * 1024); } while (0)
; #define PG8_LDB(dst, b, h) do { _Pragma("unroll") for (int n = 0; n < 2; ++n) _Pragma("unroll") for (int k = 0; k < 2; ++k) dst[n][k] = *(const PG8_LAS bf16x8*)(lds + PG8_SB(b, h) + boff + n * 2048 + k * 1024); } while (0)
; #define PG8_MMA(ai, bj, At, Bt) do { __builtin_amdgcn_s_setprio(1); _Pragma("unroll") for (int m = 0; m < 4; ++m) _Pragma("unroll") for (int n = 0; n < 2; ++n) _Pragma("unroll") for (int k = 0; k < 2; ++k) \
;         acc[ai][bj][m][n] = __builtin_amdgcn_mfma_f32_16x16x32_bf16(Bt[n][k], At[m][k], acc[ai][bj][m][n], 0, 0, 0); __builtin_amdgcn_s_setprio(0); } while (0)
; #define PG8_WAIT_V(n) asm volatile("s_waitcnt vmcnt(" #n ")" ::: "memory")
; #define PG8_BAR __builtin_amdgcn_s_barrier()
; template <class Epi, class Sched, bool ALIGN_EPI = false, bool SP2 = false>
; __device__ __forceinline__ void gemm_phase(PG8_LAS unsigned char* lds, const Gemm g, const Sched& S, const Epi& E) {
;     ...
;         for (int t = 0; t < nt; t += 2) {
;             const bool last = (t == nt - 2);
;             const char* a1 = cA + (size_t)(t + 1) * kstep;
;             const char* a2 = last ? nA : cA + (size_t)(t + 2) * kstep; const char* b2 = last ? nB : cB + (size_t)(t + 2) * kstep;
;             const char* a3 = a2 + kstep; const char* b3 = b2 + kstep;
;             if (last && has_next) S.a_ready(nxt);
;             if constexpr (SP2) {
;             PG8_LDB(B0, 0, 0); PG8_LDB(B1, 0, 1); PG8_SCHED; PG8_LDA(At, 0, 0); PG8_STAGE(PG8_SA(1, 1), a1 + hstep, voffA);
;             PG8_WAIT_V(8); PG8_WAIT_L(0); PG8_BAR; PG8_MMA(0, 0, At, B0); PG8_MMA(0, 1, At, B1); PG8_BAR; PG8_SCHED;
;             PG8_LDA(At, 0, 1); PG8_STAGE(PG8_SB(0, 0), b2, voffB); PG8_STAGE(PG8_SB(0, 1), b2 + hstep, voffB); PG8_STAGE(PG8_SA(0, 0), a2, voffA);
;             PG8_WAIT_V(8); PG8_WAIT_L(0); PG8_BAR; PG8_MMA(1, 0, At, B0); PG8_MMA(1, 1, At, B1); PG8_BAR; PG8_SCHED;
.LBB0_257:
	s_add_u32 s16, s8, 0xfffc0080
	s_addc_u32 s17, s9, -1
	s_add_i32 s18, 0, 0x10000
	s_cmp_eq_u32 s55, 12
	s_cselect_b32 s43, s14, s17
	s_cselect_b32 s42, s15, s16
	v_add_u32_e32 v0, s18, v210
	s_cselect_b32 s41, s13, s54
	s_cselect_b32 s40, s25, s53
	s_add_i32 s19, 0, 0x14000
	ds_read_b128 v[104:107], v0
	ds_read_b128 v[140:143], v0 offset:1024
	ds_read_b128 v[144:147], v0 offset:2048
	ds_read_b128 v[148:151], v0 offset:3072
	v_add_u32_e32 v0, s19, v210
	ds_read_b128 v[152:155], v0
	ds_read_b128 v[156:159], v0 offset:1024
	ds_read_b128 v[160:163], v0 offset:2048
	ds_read_b128 v[192:195], v0 offset:3072
	v_lshl_add_u64 v[2:3], s[8:9], 0, v[188:189]
	s_add_i32 m0, s44, 0xc000
	ds_read_b128 v[196:199], v212
	ds_read_b128 v[214:217], v212 offset:1024
	ds_read_b128 v[218:221], v212 offset:2048
	ds_read_b128 v[222:225], v212 offset:3072
	ds_read_b128 v[226:229], v212 offset:4096
	ds_read_b128 v[230:233], v212 offset:5120
	ds_read_b128 v[234:237], v212 offset:6144
	ds_read_b128 v[238:241], v212 offset:7168
	global_load_lds_dwordx4 v[2:3], off
	v_lshl_add_u64 v[2:3], s[8:9], 0, v[190:191]
	s_add_i32 m0, s44, 0xe000
	s_nop 0
	global_load_lds_dwordx4 v[2:3], off
	s_waitcnt vmcnt(8)
	s_waitcnt lgkmcnt(0)
	s_barrier
	s_waitcnt lgkmcnt(0)
	v_mfma_f32_16x16x32_bf16 v[136:139], v[104:107], v[196:199], v[136:139]
	v_mfma_f32_16x16x32_bf16 v[128:131], v[144:147], v[196:199], v[128:131]
	v_mfma_f32_16x16x32_bf16 v[120:123], v[104:107], v[218:221], v[120:123]
	v_mfma_f32_16x16x32_bf16 v[112:115], v[144:147], v[218:221], v[112:115]
	v_mfma_f32_16x16x32_bf16 v[100:103], v[104:107], v[226:229], v[100:103]
	v_mfma_f32_16x16x32_bf16 v[92:95], v[144:147], v[226:229], v[92:95]
	v_mfma_f32_16x16x32_bf16 v[84:87], v[104:107], v[234:237], v[84:87]
	v_mfma_f32_16x16x32_bf16 v[76:79], v[144:147], v[234:237], v[76:79]
	s_setprio 1
	v_mfma_f32_16x16x32_bf16 v[136:139], v[140:143], v[214:217], v[136:139]
	v_mfma_f32_16x16x32_bf16 v[128:131], v[148:151], v[214:217], v[128:131]
	v_mfma_f32_16x16x32_bf16 v[120:123], v[140:143], v[222:225], v[120:123]
	v_mfma_f32_16x16x32_bf16 v[112:115], v[148:151], v[222:225], v[112:115]
	v_mfma_f32_16x16x32_bf16 v[100:103], v[140:143], v[230:233], v[100:103]
	v_mfma_f32_16x16x32_bf16 v[92:95], v[148:151], v[230:233], v[92:95]
	v_mfma_f32_16x16x32_bf16 v[84:87], v[140:143], v[238:241], v[84:87]
	v_mfma_f32_16x16x32_bf16 v[76:79], v[148:151], v[238:241], v[76:79]
	s_setprio 0
	s_setprio 1
	v_mfma_f32_16x16x32_bf16 v[132:135], v[152:155], v[196:199], v[132:135]
	v_mfma_f32_16x16x32_bf16 v[124:127], v[160:163], v[196:199], v[124:127]
	v_mfma_f32_16x16x32_bf16 v[116:119], v[152:155], v[218:221], v[116:119]
	v_mfma_f32_16x16x32_bf16 v[108:111], v[160:163], v[218:221], v[108:111]
	v_mfma_f32_16x16x32_bf16 v[96:99], v[152:155], v[226:229], v[96:99]
	v_mfma_f32_16x16x32_bf16 v[88:91], v[160:163], v[226:229], v[88:91]
	v_mfma_f32_16x16x32_bf16 v[80:83], v[152:155], v[234:237], v[80:83]
	v_mfma_f32_16x16x32_bf16 v[72:75], v[160:163], v[234:237], v[72:75]
	s_barrier
	v_mfma_f32_16x16x32_bf16 v[132:135], v[156:159], v[214:217], v[132:135]
	v_mfma_f32_16x16x32_bf16 v[124:127], v[192:195], v[214:217], v[124:127]
	v_mfma_f32_16x16x32_bf16 v[116:119], v[156:159], v[222:225], v[116:119]
	v_mfma_f32_16x16x32_bf16 v[108:111], v[192:195], v[222:225], v[108:111]
	v_mfma_f32_16x16x32_bf16 v[96:99], v[156:159], v[230:233], v[96:99]
	v_mfma_f32_16x16x32_bf16 v[88:91], v[192:195], v[230:233], v[88:91]
	v_mfma_f32_16x16x32_bf16 v[80:83], v[156:159], v[238:241], v[80:83]
	v_mfma_f32_16x16x32_bf16 v[72:75], v[192:195], v[238:241], v[72:75]
	s_setprio 0
	s_add_i32 s16, s18, s36
	v_lshl_add_u64 v[2:3], s[40:41], 0, v[182:183]
	s_mov_b32 m0, s16
	ds_read_b128 v[196:199], v212 offset:16384
	ds_read_b128 v[214:217], v212 offset:17408
	ds_read_b128 v[218:221], v212 offset:18432
	ds_read_b128 v[222:225], v212 offset:19456
	ds_read_b128 v[226:229], v212 offset:20480
	ds_read_b128 v[230:233], v212 offset:21504
	ds_read_b128 v[234:237], v212 offset:22528
	ds_read_b128 v[238:241], v212 offset:23552
	global_load_lds_dwordx4 v[2:3], off
	s_add_i32 m0, s16, 0x2000
	s_add_u32 s16, s40, 0x40000
	v_lshl_add_u64 v[200:201], s[40:41], 0, v[178:179]
	s_addc_u32 s17, s41, 0
	s_add_i32 s18, s19, s36
	global_load_lds_dwordx4 v[200:201], off
	v_lshl_add_u64 v[242:243], s[16:17], 0, v[182:183]
	s_mov_b32 m0, s18
	v_lshl_add_u64 v[244:245], s[42:43], 0, v[180:181]
	global_load_lds_dwordx4 v[242:243], off
	v_lshl_add_u64 v[242:243], s[16:17], 0, v[178:179]
	s_add_i32 m0, s18, 0x2000
	s_nop 0
	global_load_lds_dwordx4 v[242:243], off
	v_lshl_add_u64 v[242:243], s[42:43], 0, v[184:185]
	s_waitcnt vmcnt(6)
	s_waitcnt lgkmcnt(0)
	s_barrier
	s_waitcnt lgkmcnt(0)
	v_mfma_f32_16x16x32_bf16 v[68:71], v[104:107], v[196:199], v[68:71]
	v_mfma_f32_16x16x32_bf16 v[60:63], v[144:147], v[196:199], v[60:63]
	v_mfma_f32_16x16x32_bf16 v[52:55], v[104:107], v[218:221], v[52:55]
	s_mov_b32 m0, s44
	v_mfma_f32_16x16x32_bf16 v[44:47], v[144:147], v[218:221], v[44:47]
	global_load_lds_dwordx4 v[242:243], off
	v_mfma_f32_16x16x32_bf16 v[36:39], v[104:107], v[226:229], v[36:39]
	v_mfma_f32_16x16x32_bf16 v[28:31], v[144:147], v[226:229], v[28:31]
	v_mfma_f32_16x16x32_bf16 v[20:23], v[104:107], v[234:237], v[20:23]
	v_mfma_f32_16x16x32_bf16 v[12:15], v[144:147], v[234:237], v[12:15]
	s_setprio 1
	v_mfma_f32_16x16x32_bf16 v[68:71], v[140:143], v[214:217], v[68:71]
	v_mfma_f32_16x16x32_bf16 v[60:63], v[148:151], v[214:217], v[60:63]
	v_mfma_f32_16x16x32_bf16 v[52:55], v[140:143], v[222:225], v[52:55]
	s_mov_b32 m0, s45
	v_mfma_f32_16x16x32_bf16 v[44:47], v[148:151], v[222:225], v[44:47]
	global_load_lds_dwordx4 v[244:245], off
	v_mfma_f32_16x16x32_bf16 v[36:39], v[140:143], v[230:233], v[36:39]
	v_mfma_f32_16x16x32_bf16 v[28:31], v[148:151], v[230:233], v[28:31]
	v_mfma_f32_16x16x32_bf16 v[20:23], v[140:143], v[238:241], v[20:23]
	v_mfma_f32_16x16x32_bf16 v[12:15], v[148:151], v[238:241], v[12:15]
	s_setprio 0
	s_setprio 1
	v_mfma_f32_16x16x32_bf16 v[64:67], v[152:155], v[196:199], v[64:67]
	v_mfma_f32_16x16x32_bf16 v[56:59], v[160:163], v[196:199], v[56:59]
	v_mfma_f32_16x16x32_bf16 v[48:51], v[152:155], v[218:221], v[48:51]
	v_mfma_f32_16x16x32_bf16 v[40:43], v[160:163], v[218:221], v[40:43]
	v_mfma_f32_16x16x32_bf16 v[32:35], v[152:155], v[226:229], v[32:35]
	v_mfma_f32_16x16x32_bf16 v[24:27], v[160:163], v[226:229], v[24:27]
	v_mfma_f32_16x16x32_bf16 v[16:19], v[152:155], v[234:237], v[16:19]
	v_mfma_f32_16x16x32_bf16 v[8:11], v[160:163], v[234:237], v[8:11]
	s_barrier
; #define PG8_STAGE(bufoff, gbase, voff) do { _Pragma("unroll") for (int _i = 0; _i < 2; ++_i) \
;         __builtin_amdgcn_global_load_lds((const unsigned*)((const char*)(gbase) + (voff)[_i]), (PG8_LAS unsigned*)(lds + (bufoff) + ldsw + _i * 8192), 16, 0, 0); } while (0)
; #define PG8_LDA(dst, b, h) do { _Pragma("unroll") for (int m = 0; m < 4; ++m) _Pragma("unroll") for (int k = 0; k < 2; ++k) dst[m][k] = *(const PG8_LAS bf16x8*)(lds + PG8_SA(b, h) + aoff + m * 2048 + k * 1024); } while (0)
; #define PG8_LDB(dst, b, h) do { _Pragma("unroll") for (int n = 0; n < 2; ++n) _Pragma("unroll") for (int k = 0; k < 2; ++k) dst[n][k] = *(const PG8_LAS bf16x8*)(lds + PG8_SB(b, h) + boff + n * 2048 + k * 1024); } while (0)
; #define PG8_MMA(ai, bj, At, Bt) do { __builtin_amdgcn_s_setprio(1); _Pragma("unroll") for (int m = 0; m < 4; ++m) _Pragma("unroll") for (int n = 0; n < 2; ++n) _Pragma("unroll") for (int k = 0; k < 2; ++k) \
;         acc[ai][bj][m][n] = __builtin_amdgcn_mfma_f32_16x16x32_bf16(Bt[n][k], At[m][k], acc[ai][bj][m][n], 0, 0, 0); __builtin_amdgcn_s_setprio(0); } while (0)
; #define PG8_WAIT_V(n) asm volatile("s_waitcnt vmcnt(" #n ")" ::: "memory")
; #define PG8_WAIT_L(n) asm volatile("s_waitcnt lgkmcnt(" #n ")" ::: "memory")
; #define PG8_BAR __builtin_amdgcn_s_barrier()
; #define PG8_SCHED __builtin_amdgcn_sched_barrier(0)
; template <class Epi, class Sched, bool ALIGN_EPI = false, bool SP2 = false>
; __device__ __forceinline__ void gemm_phase(PG8_LAS unsigned char* lds, const Gemm g, const Sched& S, const Epi& E) {
;     ...
;             PG8_WAIT_V(8); PG8_WAIT_L(0); PG8_BAR; PG8_MMA(1, 0, At, B0); PG8_MMA(1, 1, At, B1); PG8_BAR; PG8_SCHED;
;             PG8_LDB(B0, 1, 0); PG8_LDB(B1, 1, 1); PG8_SCHED; PG8_LDA(At, 1, 0); PG8_STAGE(PG8_SA(0, 1), a2 + hstep, voffA);
;             PG8_WAIT_V(8); PG8_WAIT_L(0); PG8_BAR; PG8_MMA(0, 0, At, B0); PG8_MMA(0, 1, At, B1); PG8_BAR; PG8_SCHED;
	v_mfma_f32_16x16x32_bf16 v[64:67], v[156:159], v[214:217], v[64:67]
	v_mfma_f32_16x16x32_bf16 v[56:59], v[192:195], v[214:217], v[56:59]
	v_mfma_f32_16x16x32_bf16 v[48:51], v[156:159], v[222:225], v[48:51]
	v_mfma_f32_16x16x32_bf16 v[40:43], v[192:195], v[222:225], v[40:43]
	v_mfma_f32_16x16x32_bf16 v[32:35], v[156:159], v[230:233], v[32:35]
	v_mfma_f32_16x16x32_bf16 v[24:27], v[192:195], v[230:233], v[24:27]
	v_mfma_f32_16x16x32_bf16 v[16:19], v[156:159], v[238:241], v[16:19]
	v_mfma_f32_16x16x32_bf16 v[8:11], v[192:195], v[238:241], v[8:11]
	s_setprio 0
	s_add_i32 s18, 0, 0x18000
	v_add_u32_e32 v0, s18, v210
	ds_read_b128 v[104:107], v0
	ds_read_b128 v[140:143], v0 offset:1024
	ds_read_b128 v[144:147], v0 offset:2048
	ds_read_b128 v[148:151], v0 offset:3072
	v_add_u32_e32 v0, s33, v210
	ds_read_b128 v[152:155], v0
	ds_read_b128 v[156:159], v0 offset:1024
	ds_read_b128 v[160:163], v0 offset:2048
	ds_read_b128 v[192:195], v0 offset:3072
	s_add_u32 s16, s42, 0x40000
	s_addc_u32 s17, s43, 0
	s_mov_b32 m0, s46
	v_lshl_add_u64 v[246:247], s[16:17], 0, v[184:185]
	ds_read_b128 v[196:199], v212 offset:32768
	ds_read_b128 v[214:217], v212 offset:33792
	ds_read_b128 v[218:221], v212 offset:34816
	ds_read_b128 v[222:225], v212 offset:35840
	ds_read_b128 v[226:229], v212 offset:36864
	ds_read_b128 v[230:233], v212 offset:37888
	ds_read_b128 v[234:237], v212 offset:38912
	ds_read_b128 v[238:241], v212 offset:39936
	global_load_lds_dwordx4 v[246:247], off
	v_lshl_add_u64 v[246:247], s[16:17], 0, v[180:181]
	s_mov_b32 m0, s47
	s_nop 0
	global_load_lds_dwordx4 v[246:247], off
	s_waitcnt vmcnt(8)
	s_waitcnt lgkmcnt(0)
	s_barrier
	s_waitcnt lgkmcnt(0)
	v_mfma_f32_16x16x32_bf16 v[136:139], v[104:107], v[196:199], v[136:139]
	v_mfma_f32_16x16x32_bf16 v[128:131], v[144:147], v[196:199], v[128:131]
	v_mfma_f32_16x16x32_bf16 v[120:123], v[104:107], v[218:221], v[120:123]
	v_mfma_f32_16x16x32_bf16 v[112:115], v[144:147], v[218:221], v[112:115]
	v_mfma_f32_16x16x32_bf16 v[100:103], v[104:107], v[226:229], v[100:103]
	v_mfma_f32_16x16x32_bf16 v[92:95], v[144:147], v[226:229], v[92:95]
	v_mfma_f32_16x16x32_bf16 v[84:87], v[104:107], v[234:237], v[84:87]
	v_mfma_f32_16x16x32_bf16 v[76:79], v[144:147], v[234:237], v[76:79]
	s_setprio 1
	v_mfma_f32_16x16x32_bf16 v[136:139], v[140:143], v[214:217], v[136:139]
	v_mfma_f32_16x16x32_bf16 v[128:131], v[148:151], v[214:217], v[128:131]
	v_mfma_f32_16x16x32_bf16 v[120:123], v[140:143], v[222:225], v[120:123]
	v_mfma_f32_16x16x32_bf16 v[112:115], v[148:151], v[222:225], v[112:115]
	v_mfma_f32_16x16x32_bf16 v[100:103], v[140:143], v[230:233], v[100:103]
	v_mfma_f32_16x16x32_bf16 v[92:95], v[148:151], v[230:233], v[92:95]
	v_mfma_f32_16x16x32_bf16 v[84:87], v[140:143], v[238:241], v[84:87]
	v_mfma_f32_16x16x32_bf16 v[76:79], v[148:151], v[238:241], v[76:79]
	s_setprio 0
	s_setprio 1
	v_mfma_f32_16x16x32_bf16 v[132:135], v[152:155], v[196:199], v[132:135]
	v_mfma_f32_16x16x32_bf16 v[124:127], v[160:163], v[196:199], v[124:127]
	v_mfma_f32_16x16x32_bf16 v[116:119], v[152:155], v[218:221], v[116:119]
	v_mfma_f32_16x16x32_bf16 v[108:111], v[160:163], v[218:221], v[108:111]
	v_mfma_f32_16x16x32_bf16 v[96:99], v[152:155], v[226:229], v[96:99]
	v_mfma_f32_16x16x32_bf16 v[88:91], v[160:163], v[226:229], v[88:91]
	v_mfma_f32_16x16x32_bf16 v[80:83], v[152:155], v[234:237], v[80:83]
	v_mfma_f32_16x16x32_bf16 v[72:75], v[160:163], v[234:237], v[72:75]
	s_barrier
; #define PG8_STAGE(bufoff, gbase, voff) do { _Pragma("unroll") for (int _i = 0; _i < 2; ++_i) \
;         __builtin_amdgcn_global_load_lds((const unsigned*)((const char*)(gbase) + (voff)[_i]), (PG8_LAS unsigned*)(lds + (bufoff) + ldsw + _i * 8192), 16, 0, 0); } while (0)
; #define PG8_LDA(dst, b, h) do { _Pragma("unroll") for (int m = 0; m < 4; ++m) _Pragma("unroll") for (int k = 0; k < 2; ++k) dst[m][k] = *(const PG8_LAS bf16x8*)(lds + PG8_SA(b, h) + aoff + m * 2048 + k * 1024); } while (0)
; #define PG8_MMA(ai, bj, At, Bt) do { __builtin_amdgcn_s_setprio(1); _Pragma("unroll") for (int m = 0; m < 4; ++m) _Pragma("unroll") for (int n = 0; n < 2; ++n) _Pragma("unroll") for (int k = 0; k < 2; ++k) \
;         acc[ai][bj][m][n] = __builtin_amdgcn_mfma_f32_16x16x32_bf16(Bt[n][k], At[m][k], acc[ai][bj][m][n], 0, 0, 0); __builtin_amdgcn_s_setprio(0); } while (0)
; #define PG8_WAIT_V(n) asm volatile("s_waitcnt vmcnt(" #n ")" ::: "memory")
; #define PG8_WAIT_L(n) asm volatile("s_waitcnt lgkmcnt(" #n ")" ::: "memory")
; #define PG8_BAR __builtin_amdgcn_s_barrier()
; #define PG8_SCHED __builtin_amdgcn_sched_barrier(0)
; template <class Epi, class Sched, bool ALIGN_EPI = false, bool SP2 = false>
; __device__ __forceinline__ void gemm_phase(PG8_LAS unsigned char* lds, const Gemm g, const Sched& S, const Epi& E) {
;     ...
;             PG8_WAIT_V(8); PG8_WAIT_L(0); PG8_BAR; PG8_MMA(0, 0, At, B0); PG8_MMA(0, 1, At, B1); PG8_BAR; PG8_SCHED;
;             PG8_LDA(At, 1, 1); PG8_STAGE(PG8_SB(1, 0), b3, voffB); PG8_STAGE(PG8_SB(1, 1), b3 + hstep, voffB); PG8_STAGE(PG8_SA(1, 0), a3, voffA);
;             PG8_WAIT_V(8); PG8_WAIT_L(0); PG8_BAR; PG8_MMA(1, 0, At, B0); PG8_MMA(1, 1, At, B1); PG8_BAR; PG8_SCHED;
	v_mfma_f32_16x16x32_bf16 v[132:135], v[156:159], v[214:217], v[132:135]
	v_mfma_f32_16x16x32_bf16 v[124:127], v[192:195], v[214:217], v[124:127]
	v_mfma_f32_16x16x32_bf16 v[116:119], v[156:159], v[222:225], v[116:119]
	v_mfma_f32_16x16x32_bf16 v[108:111], v[192:195], v[222:225], v[108:111]
	v_mfma_f32_16x16x32_bf16 v[96:99], v[156:159], v[230:233], v[96:99]
	v_mfma_f32_16x16x32_bf16 v[88:91], v[192:195], v[230:233], v[88:91]
	v_mfma_f32_16x16x32_bf16 v[80:83], v[156:159], v[238:241], v[80:83]
	v_mfma_f32_16x16x32_bf16 v[72:75], v[192:195], v[238:241], v[72:75]
	s_setprio 0
	s_add_i32 s16, s18, s36
	v_lshl_add_u64 v[2:3], v[2:3], 0, s[20:21]
	s_mov_b32 m0, s16
	ds_read_b128 v[196:199], v212 offset:49152
	ds_read_b128 v[214:217], v212 offset:50176
	ds_read_b128 v[218:221], v212 offset:51200
	ds_read_b128 v[222:225], v212 offset:52224
	ds_read_b128 v[226:229], v212 offset:53248
	ds_read_b128 v[230:233], v212 offset:54272
	ds_read_b128 v[234:237], v212 offset:55296
	ds_read_b128 v[238:241], v212 offset:56320
	global_load_lds_dwordx4 v[2:3], off
	s_add_i32 m0, s16, 0x2000
	s_add_u32 s16, s40, 0x40080
	v_lshl_add_u64 v[2:3], v[200:201], 0, s[20:21]
	s_addc_u32 s17, s41, 0
	s_add_i32 s18, s33, s36
	global_load_lds_dwordx4 v[2:3], off
	v_lshl_add_u64 v[2:3], s[16:17], 0, v[182:183]
	s_mov_b32 m0, s18
	s_nop 0
	global_load_lds_dwordx4 v[2:3], off
	v_lshl_add_u64 v[2:3], s[16:17], 0, v[178:179]
	s_add_i32 m0, s18, 0x2000
	s_nop 0
	global_load_lds_dwordx4 v[2:3], off
	v_lshl_add_u64 v[2:3], v[242:243], 0, s[20:21]
	v_lshl_add_u64 v[244:245], v[244:245], 0, s[20:21]
	s_waitcnt vmcnt(6)
	s_waitcnt lgkmcnt(0)
	s_barrier
	s_waitcnt lgkmcnt(0)
	v_mfma_f32_16x16x32_bf16 v[68:71], v[104:107], v[196:199], v[68:71]
	v_mfma_f32_16x16x32_bf16 v[60:63], v[144:147], v[196:199], v[60:63]
	v_mfma_f32_16x16x32_bf16 v[52:55], v[104:107], v[218:221], v[52:55]
	s_mov_b32 m0, s48
	v_mfma_f32_16x16x32_bf16 v[44:47], v[144:147], v[218:221], v[44:47]
	global_load_lds_dwordx4 v[2:3], off
	v_mfma_f32_16x16x32_bf16 v[36:39], v[104:107], v[226:229], v[36:39]
	v_mfma_f32_16x16x32_bf16 v[28:31], v[144:147], v[226:229], v[28:31]
	v_mfma_f32_16x16x32_bf16 v[20:23], v[104:107], v[234:237], v[20:23]
	v_mfma_f32_16x16x32_bf16 v[12:15], v[144:147], v[234:237], v[12:15]
	s_setprio 1
	v_mfma_f32_16x16x32_bf16 v[68:71], v[140:143], v[214:217], v[68:71]
	v_mfma_f32_16x16x32_bf16 v[60:63], v[148:151], v[214:217], v[60:63]
	v_mfma_f32_16x16x32_bf16 v[52:55], v[140:143], v[222:225], v[52:55]
	s_mov_b32 m0, s49
	v_mfma_f32_16x16x32_bf16 v[44:47], v[148:151], v[222:225], v[44:47]
	global_load_lds_dwordx4 v[244:245], off
	v_mfma_f32_16x16x32_bf16 v[36:39], v[140:143], v[230:233], v[36:39]
	v_mfma_f32_16x16x32_bf16 v[28:31], v[148:151], v[230:233], v[28:31]
	v_mfma_f32_16x16x32_bf16 v[20:23], v[140:143], v[238:241], v[20:23]
	v_mfma_f32_16x16x32_bf16 v[12:15], v[148:151], v[238:241], v[12:15]
	s_setprio 0
	s_setprio 1
	v_mfma_f32_16x16x32_bf16 v[64:67], v[152:155], v[196:199], v[64:67]
	v_mfma_f32_16x16x32_bf16 v[56:59], v[160:163], v[196:199], v[56:59]
	v_mfma_f32_16x16x32_bf16 v[48:51], v[152:155], v[218:221], v[48:51]
	v_mfma_f32_16x16x32_bf16 v[40:43], v[160:163], v[218:221], v[40:43]
	v_mfma_f32_16x16x32_bf16 v[32:35], v[152:155], v[226:229], v[32:35]
	v_mfma_f32_16x16x32_bf16 v[24:27], v[160:163], v[226:229], v[24:27]
	v_mfma_f32_16x16x32_bf16 v[16:19], v[152:155], v[234:237], v[16:19]
	v_mfma_f32_16x16x32_bf16 v[8:11], v[160:163], v[234:237], v[8:11]
	s_barrier
	v_mfma_f32_16x16x32_bf16 v[64:67], v[156:159], v[214:217], v[64:67]
	v_mfma_f32_16x16x32_bf16 v[56:59], v[192:195], v[214:217], v[56:59]
	v_mfma_f32_16x16x32_bf16 v[48:51], v[156:159], v[222:225], v[48:51]
	v_mfma_f32_16x16x32_bf16 v[40:43], v[192:195], v[222:225], v[40:43]
	v_mfma_f32_16x16x32_bf16 v[32:35], v[156:159], v[230:233], v[32:35]
	v_mfma_f32_16x16x32_bf16 v[24:27], v[192:195], v[230:233], v[24:27]
	v_mfma_f32_16x16x32_bf16 v[16:19], v[156:159], v[238:241], v[16:19]
	v_mfma_f32_16x16x32_bf16 v[8:11], v[192:195], v[238:241], v[8:11]
	s_setprio 0
	s_add_i32 s55, s55, 2
	s_add_u32 s8, s8, 0x100
	s_addc_u32 s9, s9, 0
	s_add_u32 s53, s53, 0x100
	s_addc_u32 s54, s54, 0
	s_cmp_gt_u32 s55, 13
	s_cbranch_scc0 .LBB0_257
	s_and_b64 vcc, exec, s[10:11]
	s_cbranch_vccz .LBB0_260
	s_barrier
	s_setprio 1
